# P0: non-temporal (nt) loads for the single-use f32 inputs (weights in the transposes, x in the rms rows) so they do not displace the bf16 operands in L2 / memory-side cache
# speedup vs baseline: 1.0186x; 1.0186x over previous
.Lp0tA_nog:
	global_load_dword v32, v6, s[76:77] nt
	s_add_u32 s76, s76, s1
	s_addc_u32 s77, s77, 0
	global_load_dword v33, v6, s[76:77] nt
	s_add_u32 s76, s76, s1
	s_addc_u32 s77, s77, 0
	global_load_dword v34, v6, s[76:77] nt
	s_add_u32 s76, s76, s1
	s_addc_u32 s77, s77, 0
	global_load_dword v35, v6, s[76:77] nt
	s_add_u32 s76, s76, s1
	s_addc_u32 s77, s77, 0
	global_load_dword v36, v6, s[76:77] nt
	s_add_u32 s76, s76, s1
	s_addc_u32 s77, s77, 0
	global_load_dword v37, v6, s[76:77] nt
	s_add_u32 s76, s76, s1
	s_addc_u32 s77, s77, 0
	global_load_dword v38, v6, s[76:77] nt
	s_add_u32 s76, s76, s1
	s_addc_u32 s77, s77, 0
	global_load_dword v39, v6, s[76:77] nt
	s_add_u32 s76, s76, s1
	s_addc_u32 s77, s77, 0
	global_load_dword v40, v6, s[76:77] nt
	s_add_u32 s76, s76, s1
	s_addc_u32 s77, s77, 0
	global_load_dword v41, v6, s[76:77] nt
	s_add_u32 s76, s76, s1
	s_addc_u32 s77, s77, 0
	global_load_dword v42, v6, s[76:77] nt
	s_add_u32 s76, s76, s1
	s_addc_u32 s77, s77, 0
	global_load_dword v43, v6, s[76:77] nt
	s_add_u32 s76, s76, s1
	s_addc_u32 s77, s77, 0
	global_load_dword v44, v6, s[76:77] nt
	s_add_u32 s76, s76, s1
	s_addc_u32 s77, s77, 0
	global_load_dword v45, v6, s[76:77] nt
	s_add_u32 s76, s76, s1
	s_addc_u32 s77, s77, 0
	global_load_dword v46, v6, s[76:77] nt
	s_add_u32 s76, s76, s1
	s_addc_u32 s77, s77, 0
	global_load_dword v47, v6, s[76:77] nt
	s_add_u32 s76, s76, s1
	s_addc_u32 s77, s77, 0
	global_load_dword v48, v6, s[76:77] nt
	s_add_u32 s76, s76, s1
	s_addc_u32 s77, s77, 0
	global_load_dword v49, v6, s[76:77] nt
	s_add_u32 s76, s76, s1
	s_addc_u32 s77, s77, 0
	global_load_dword v50, v6, s[76:77] nt
	s_add_u32 s76, s76, s1
	s_addc_u32 s77, s77, 0
	global_load_dword v51, v6, s[76:77] nt
	s_add_u32 s76, s76, s1
	s_addc_u32 s77, s77, 0
	global_load_dword v52, v6, s[76:77] nt
	s_add_u32 s76, s76, s1
	s_addc_u32 s77, s77, 0
	global_load_dword v53, v6, s[76:77] nt
	s_add_u32 s76, s76, s1
	s_addc_u32 s77, s77, 0
	global_load_dword v54, v6, s[76:77] nt
	s_add_u32 s76, s76, s1
	s_addc_u32 s77, s77, 0
	global_load_dword v55, v6, s[76:77] nt
	s_add_u32 s76, s76, s1
	s_addc_u32 s77, s77, 0
	global_load_dword v56, v6, s[76:77] nt
	s_add_u32 s76, s76, s1
	s_addc_u32 s77, s77, 0
	global_load_dword v57, v6, s[76:77] nt
	s_add_u32 s76, s76, s1
	s_addc_u32 s77, s77, 0
	global_load_dword v58, v6, s[76:77] nt
	s_add_u32 s76, s76, s1
	s_addc_u32 s77, s77, 0
	global_load_dword v59, v6, s[76:77] nt
	s_add_u32 s76, s76, s1
	s_addc_u32 s77, s77, 0
	global_load_dword v60, v6, s[76:77] nt
	s_add_u32 s76, s76, s1
	s_addc_u32 s77, s77, 0
	global_load_dword v61, v6, s[76:77] nt
	s_add_u32 s76, s76, s1
	s_addc_u32 s77, s77, 0
	global_load_dword v62, v6, s[76:77] nt
	s_add_u32 s76, s76, s1
	s_addc_u32 s77, s77, 0
	global_load_dword v63, v6, s[76:77] nt
	s_mov_b32 s85, 1
	s_add_u32 s7, s7, s6

.Lp0tB_nog:
	global_load_dword v128, v6, s[76:77] nt
	s_add_u32 s76, s76, s1
	s_addc_u32 s77, s77, 0
	global_load_dword v129, v6, s[76:77] nt
	s_add_u32 s76, s76, s1
	s_addc_u32 s77, s77, 0
	global_load_dword v130, v6, s[76:77] nt
	s_add_u32 s76, s76, s1
	s_addc_u32 s77, s77, 0
	global_load_dword v131, v6, s[76:77] nt
	s_add_u32 s76, s76, s1
	s_addc_u32 s77, s77, 0
	global_load_dword v132, v6, s[76:77] nt
	s_add_u32 s76, s76, s1
	s_addc_u32 s77, s77, 0
	global_load_dword v133, v6, s[76:77] nt
	s_add_u32 s76, s76, s1
	s_addc_u32 s77, s77, 0
	global_load_dword v134, v6, s[76:77] nt
	s_add_u32 s76, s76, s1
	s_addc_u32 s77, s77, 0
	global_load_dword v135, v6, s[76:77] nt
	s_add_u32 s76, s76, s1
	s_addc_u32 s77, s77, 0
	global_load_dword v136, v6, s[76:77] nt
	s_add_u32 s76, s76, s1
	s_addc_u32 s77, s77, 0
	global_load_dword v137, v6, s[76:77] nt
	s_add_u32 s76, s76, s1
	s_addc_u32 s77, s77, 0
	global_load_dword v138, v6, s[76:77] nt
	s_add_u32 s76, s76, s1
	s_addc_u32 s77, s77, 0
	global_load_dword v139, v6, s[76:77] nt
	s_add_u32 s76, s76, s1
	s_addc_u32 s77, s77, 0
	global_load_dword v140, v6, s[76:77] nt
	s_add_u32 s76, s76, s1
	s_addc_u32 s77, s77, 0
	global_load_dword v141, v6, s[76:77] nt
	s_add_u32 s76, s76, s1
	s_addc_u32 s77, s77, 0
	global_load_dword v142, v6, s[76:77] nt
	s_add_u32 s76, s76, s1
	s_addc_u32 s77, s77, 0
	global_load_dword v143, v6, s[76:77] nt
	s_add_u32 s76, s76, s1
	s_addc_u32 s77, s77, 0
	global_load_dword v144, v6, s[76:77] nt
	s_add_u32 s76, s76, s1
	s_addc_u32 s77, s77, 0
	global_load_dword v145, v6, s[76:77] nt
	s_add_u32 s76, s76, s1
	s_addc_u32 s77, s77, 0
	global_load_dword v146, v6, s[76:77] nt
	s_add_u32 s76, s76, s1
	s_addc_u32 s77, s77, 0
	global_load_dword v147, v6, s[76:77] nt
	s_add_u32 s76, s76, s1
	s_addc_u32 s77, s77, 0
	global_load_dword v148, v6, s[76:77] nt
	s_add_u32 s76, s76, s1
	s_addc_u32 s77, s77, 0
	global_load_dword v149, v6, s[76:77] nt
	s_add_u32 s76, s76, s1
	s_addc_u32 s77, s77, 0
	global_load_dword v150, v6, s[76:77] nt
	s_add_u32 s76, s76, s1
	s_addc_u32 s77, s77, 0
	global_load_dword v151, v6, s[76:77] nt
	s_add_u32 s76, s76, s1
	s_addc_u32 s77, s77, 0
	global_load_dword v152, v6, s[76:77] nt
	s_add_u32 s76, s76, s1
	s_addc_u32 s77, s77, 0
	global_load_dword v153, v6, s[76:77] nt
	s_add_u32 s76, s76, s1
	s_addc_u32 s77, s77, 0
	global_load_dword v154, v6, s[76:77] nt
	s_add_u32 s76, s76, s1
	s_addc_u32 s77, s77, 0
	global_load_dword v155, v6, s[76:77] nt
	s_add_u32 s76, s76, s1
	s_addc_u32 s77, s77, 0
	global_load_dword v156, v6, s[76:77] nt
	s_add_u32 s76, s76, s1
	s_addc_u32 s77, s77, 0
	global_load_dword v157, v6, s[76:77] nt
	s_add_u32 s76, s76, s1
	s_addc_u32 s77, s77, 0
	global_load_dword v158, v6, s[76:77] nt
	s_add_u32 s76, s76, s1
	s_addc_u32 s77, s77, 0
	global_load_dword v159, v6, s[76:77] nt
	s_mov_b32 s84, 1
	s_add_u32 s7, s7, s6

.Lp0t_done:
.LBB0_91:
	s_cmpk_gt_i32 s4, 0x3fff
	s_cbranch_scc1 .LBB0_94
	s_waitcnt lgkmcnt(0)
	v_lshlrev_b32_e32 v0, 4, v204
	v_lshlrev_b32_e32 v1, 3, v204
	v_mov_b32_e32 v28, 0x358637bd
	s_add_u32 s0, s38, 0x1000
	s_addc_u32 s1, s39, 0
	global_load_dwordx4 v[96:99], v0, s[0:1] offset:-4096
	global_load_dwordx4 v[100:103], v0, s[0:1] offset:-3072
	global_load_dwordx4 v[104:107], v0, s[0:1] offset:-2048
	global_load_dwordx4 v[108:111], v0, s[0:1] offset:-1024
	global_load_dwordx4 v[112:115], v0, s[0:1] offset:0
	global_load_dwordx4 v[116:119], v0, s[0:1] offset:1024
	global_load_dwordx4 v[120:123], v0, s[0:1] offset:2048
	global_load_dwordx4 v[124:127], v0, s[0:1] offset:3072
	s_lshl_b32 s3, s4, 13
	s_add_u32 s8, s36, s3
	s_addc_u32 s9, s37, 0
	s_add_u32 s8, s8, 0x1000
	s_addc_u32 s9, s9, 0
	s_lshl_b32 s3, s4, 12
	s_add_u32 s10, s28, s3
	s_addc_u32 s11, s29, 0
	s_add_u32 s10, s10, 0x6200000
	s_addc_u32 s11, s11, 0
	s_lshl_b32 s7, s6, 13
	s_lshl_b32 s5, s6, 12
	global_load_dwordx4 v[32:35], v0, s[8:9] offset:-4096 nt
	global_load_dwordx4 v[36:39], v0, s[8:9] offset:-3072 nt
	global_load_dwordx4 v[40:43], v0, s[8:9] offset:-2048 nt
	global_load_dwordx4 v[44:47], v0, s[8:9] offset:-1024 nt
	global_load_dwordx4 v[48:51], v0, s[8:9] offset:0 nt
	global_load_dwordx4 v[52:55], v0, s[8:9] offset:1024 nt
	global_load_dwordx4 v[56:59], v0, s[8:9] offset:2048 nt
	global_load_dwordx4 v[60:63], v0, s[8:9] offset:3072 nt
	s_mov_b32 s3, 0
.Lp0r_loop:
	s_add_i32 s4, s4, s6
	s_cmp_lt_i32 s4, 0x4000
	s_cselect_b32 s0, 1, 0
	s_cbranch_scc0 .Lp0r_a_nonext
	s_add_u32 s8, s8, s7
	s_addc_u32 s9, s9, 0
	global_load_dwordx4 v[64:67], v0, s[8:9] offset:-4096 nt
	global_load_dwordx4 v[68:71], v0, s[8:9] offset:-3072 nt
	global_load_dwordx4 v[72:75], v0, s[8:9] offset:-2048 nt
	global_load_dwordx4 v[76:79], v0, s[8:9] offset:-1024 nt
	global_load_dwordx4 v[80:83], v0, s[8:9] offset:0 nt
	global_load_dwordx4 v[84:87], v0, s[8:9] offset:1024 nt
	global_load_dwordx4 v[88:91], v0, s[8:9] offset:2048 nt
	global_load_dwordx4 v[92:95], v0, s[8:9] offset:3072 nt

.Lp0r_a_go:
	v_pk_mul_f32 v[2:3], v[32:33], v[32:33]
	v_pk_mul_f32 v[4:5], v[34:35], v[34:35]
	v_pk_fma_f32 v[2:3], v[36:37], v[36:37], v[2:3]
	v_pk_fma_f32 v[4:5], v[38:39], v[38:39], v[4:5]
	v_pk_fma_f32 v[2:3], v[40:41], v[40:41], v[2:3]
	v_pk_fma_f32 v[4:5], v[42:43], v[42:43], v[4:5]
	v_pk_fma_f32 v[2:3], v[44:45], v[44:45], v[2:3]
	v_pk_fma_f32 v[4:5], v[46:47], v[46:47], v[4:5]
	v_pk_fma_f32 v[2:3], v[48:49], v[48:49], v[2:3]
	v_pk_fma_f32 v[4:5], v[50:51], v[50:51], v[4:5]
	v_pk_fma_f32 v[2:3], v[52:53], v[52:53], v[2:3]
	v_pk_fma_f32 v[4:5], v[54:55], v[54:55], v[4:5]
	v_pk_fma_f32 v[2:3], v[56:57], v[56:57], v[2:3]
	v_pk_fma_f32 v[4:5], v[58:59], v[58:59], v[4:5]
	v_pk_fma_f32 v[2:3], v[60:61], v[60:61], v[2:3]
	v_pk_fma_f32 v[4:5], v[62:63], v[62:63], v[4:5]
	v_pk_add_f32 v[2:3], v[2:3], v[4:5]
	s_nop 0
	v_add_f32_e32 v2, v2, v3
	s_nop 1
	v_add_f32_dpp v3, v2, v2 quad_perm:[1,0,3,2] row_mask:0xf bank_mask:0xf
	s_nop 1
	v_add_f32_dpp v2, v3, v3 quad_perm:[2,3,0,1] row_mask:0xf bank_mask:0xf
	s_nop 1
	v_add_f32_dpp v3, v2, v2 row_ror:4 row_mask:0xf bank_mask:0xf
	s_nop 1
	v_add_f32_dpp v2, v3, v3 row_ror:8 row_mask:0xf bank_mask:0xf
	s_nop 1
	v_readlane_b32 s100, v2, 0
	v_readlane_b32 s101, v2, 16
	v_readlane_b32 vcc_lo, v2, 32
	v_readlane_b32 vcc_hi, v2, 48
	v_mov_b32_e32 v3, s100
	v_add_f32_e32 v3, s101, v3
	v_add_f32_e32 v3, vcc_lo, v3
	v_add_f32_e32 v3, vcc_hi, v3
	v_fmamk_f32 v2, v3, 0x3a000000, v28
	v_mul_f32_e32 v3, 0x4b800000, v2
	v_cmp_gt_f32_e32 vcc, 0x800000, v2
	s_nop 1
	v_cndmask_b32_e32 v2, v2, v3, vcc
	v_rsq_f32_e32 v2, v2
	s_nop 0
	v_mul_f32_e32 v3, 0x45800000, v2
	v_cndmask_b32_e32 v2, v2, v3, vcc
	v_pk_mul_f32 v[32:33], v[32:33], v[2:3] op_sel_hi:[1,0]
	v_pk_mul_f32 v[34:35], v[34:35], v[2:3] op_sel_hi:[1,0]
	v_pk_mul_f32 v[32:33], v[32:33], v[96:97]
	v_pk_mul_f32 v[34:35], v[34:35], v[98:99]
	v_cvt_pk_bf16_f32 v6, v32, v33
	v_cvt_pk_bf16_f32 v7, v34, v35
	global_store_dwordx2 v1, v[6:7], s[10:11]
	v_pk_mul_f32 v[36:37], v[36:37], v[2:3] op_sel_hi:[1,0]
	v_pk_mul_f32 v[38:39], v[38:39], v[2:3] op_sel_hi:[1,0]
	v_pk_mul_f32 v[36:37], v[36:37], v[100:101]
	v_pk_mul_f32 v[38:39], v[38:39], v[102:103]
	v_cvt_pk_bf16_f32 v8, v36, v37
	v_cvt_pk_bf16_f32 v9, v38, v39
	global_store_dwordx2 v1, v[8:9], s[10:11] offset:512
	v_pk_mul_f32 v[40:41], v[40:41], v[2:3] op_sel_hi:[1,0]
	v_pk_mul_f32 v[42:43], v[42:43], v[2:3] op_sel_hi:[1,0]
	v_pk_mul_f32 v[40:41], v[40:41], v[104:105]
	v_pk_mul_f32 v[42:43], v[42:43], v[106:107]
	v_cvt_pk_bf16_f32 v6, v40, v41
	v_cvt_pk_bf16_f32 v7, v42, v43
	global_store_dwordx2 v1, v[6:7], s[10:11] offset:1024
	v_pk_mul_f32 v[44:45], v[44:45], v[2:3] op_sel_hi:[1,0]
	v_pk_mul_f32 v[46:47], v[46:47], v[2:3] op_sel_hi:[1,0]
	v_pk_mul_f32 v[44:45], v[44:45], v[108:109]
	v_pk_mul_f32 v[46:47], v[46:47], v[110:111]
	v_cvt_pk_bf16_f32 v8, v44, v45
	v_cvt_pk_bf16_f32 v9, v46, v47
	global_store_dwordx2 v1, v[8:9], s[10:11] offset:1536
	v_pk_mul_f32 v[48:49], v[48:49], v[2:3] op_sel_hi:[1,0]
	v_pk_mul_f32 v[50:51], v[50:51], v[2:3] op_sel_hi:[1,0]
	v_pk_mul_f32 v[48:49], v[48:49], v[112:113]
	v_pk_mul_f32 v[50:51], v[50:51], v[114:115]
	v_cvt_pk_bf16_f32 v6, v48, v49
	v_cvt_pk_bf16_f32 v7, v50, v51
	global_store_dwordx2 v1, v[6:7], s[10:11] offset:2048
	v_pk_mul_f32 v[52:53], v[52:53], v[2:3] op_sel_hi:[1,0]
	v_pk_mul_f32 v[54:55], v[54:55], v[2:3] op_sel_hi:[1,0]
	v_pk_mul_f32 v[52:53], v[52:53], v[116:117]
	v_pk_mul_f32 v[54:55], v[54:55], v[118:119]
	v_cvt_pk_bf16_f32 v8, v52, v53
	v_cvt_pk_bf16_f32 v9, v54, v55
	global_store_dwordx2 v1, v[8:9], s[10:11] offset:2560
	v_pk_mul_f32 v[56:57], v[56:57], v[2:3] op_sel_hi:[1,0]
	v_pk_mul_f32 v[58:59], v[58:59], v[2:3] op_sel_hi:[1,0]
	v_pk_mul_f32 v[56:57], v[56:57], v[120:121]
	v_pk_mul_f32 v[58:59], v[58:59], v[122:123]
	v_cvt_pk_bf16_f32 v6, v56, v57
	v_cvt_pk_bf16_f32 v7, v58, v59
	global_store_dwordx2 v1, v[6:7], s[10:11] offset:3072
	v_pk_mul_f32 v[60:61], v[60:61], v[2:3] op_sel_hi:[1,0]
	v_pk_mul_f32 v[62:63], v[62:63], v[2:3] op_sel_hi:[1,0]
	v_pk_mul_f32 v[60:61], v[60:61], v[124:125]
	v_pk_mul_f32 v[62:63], v[62:63], v[126:127]
	v_cvt_pk_bf16_f32 v8, v60, v61
	v_cvt_pk_bf16_f32 v9, v62, v63
	global_store_dwordx2 v1, v[8:9], s[10:11] offset:3584
	s_add_u32 s10, s10, s5
	s_addc_u32 s11, s11, 0
	s_mov_b32 s3, 1
	s_cmp_eq_u32 s0, 0
	s_cbranch_scc1 .LBB0_94
	s_add_i32 s4, s4, s6
	s_cmp_lt_i32 s4, 0x4000
	s_cselect_b32 s0, 1, 0
	s_cbranch_scc0 .Lp0r_b_nonext
	s_add_u32 s8, s8, s7
	s_addc_u32 s9, s9, 0
	global_load_dwordx4 v[32:35], v0, s[8:9] offset:-4096 nt
	global_load_dwordx4 v[36:39], v0, s[8:9] offset:-3072 nt
	global_load_dwordx4 v[40:43], v0, s[8:9] offset:-2048 nt
	global_load_dwordx4 v[44:47], v0, s[8:9] offset:-1024 nt
	global_load_dwordx4 v[48:51], v0, s[8:9] offset:0 nt
	global_load_dwordx4 v[52:55], v0, s[8:9] offset:1024 nt
	global_load_dwordx4 v[56:59], v0, s[8:9] offset:2048 nt
	global_load_dwordx4 v[60:63], v0, s[8:9] offset:3072 nt
